# v48 + prep prologue: 80-step serialized LoRA-fragment load ladder replaced by batched double-buffered loads
# speedup vs baseline: 1.0051x; 1.0033x over previous
.LBB0_843:
	s_or_b64 exec, exec, s[4:5]
	v_readlane_b32 s4, v255, 30
	s_waitcnt lgkmcnt(0)
	s_barrier
	s_ashr_i32 s10, s56, 1
	v_mov_b32_e32 v34, v212
	v_readlane_b32 s18, v254, 9
	v_lshl_add_u32 v2, s10, 9, v34
	v_readlane_b32 s68, v254, 29
	s_mov_b32 s15, s18
	v_ashrrev_i32_e32 v3, 31, v2
	v_readlane_b32 s70, v254, 31
	v_readlane_b32 s71, v254, 32
	v_readlane_b32 s16, v254, 0
	v_lshlrev_b64 v[2:3], 2, v[2:3]
	v_readlane_b32 s74, v254, 35
	v_readlane_b32 s75, v254, 36
	s_mov_b32 s15, s16
	v_lshl_add_u64 v[4:5], s[70:71], 0, v[2:3]
	global_load_dword v0, v[4:5], off
	v_lshl_add_u64 v[4:5], s[74:75], 0, v[2:3]
	global_load_dword v4, v[4:5], off
	v_readlane_b32 s80, v254, 41
	v_readlane_b32 s81, v254, 42
	v_lshl_add_u32 v6, v34, 2, 0
	v_readlane_b32 s82, v254, 43
	v_readlane_b32 s83, v254, 44
	v_writelane_b32 v255, s4, 30
	s_ashr_i32 s11, s10, 31
	s_mul_i32 s4, s10, 0x1a80
	s_mul_hi_i32 s5, s10, 0x1a80
	v_readlane_b32 s69, v254, 30
	s_add_u32 s4, s68, s4
	v_readlane_b32 s72, v254, 33
	s_addc_u32 s5, s69, s5
	s_lshl_b64 s[6:7], s[10:11], 16
	v_readlane_b32 s73, v254, 34
	s_add_u32 s12, s72, s6
	v_readlane_b32 s76, v254, 37
	s_addc_u32 s13, s73, s7
	v_readlane_b32 s77, v254, 38
	s_add_u32 s8, s76, s6
	v_readlane_b32 s78, v254, 39
	s_addc_u32 s9, s77, s7
	s_mul_i32 s6, s10, 0x30000
	v_readlane_b32 s79, v254, 40
	s_mul_hi_i32 s7, s10, 0x30000
	s_add_u32 s6, s78, s6
	s_addc_u32 s7, s79, s7
	v_ashrrev_i32_e32 v35, 31, v34
	s_movk_i32 s25, 0x1000
	v_readfirstlane_b32 s11, v34
	v_and_b32_e32 v171, 15, v34
	v_bfe_u32 v41, v34, 4, 2
	s_and_b32 s10, s11, 0xffffffc0
	s_ashr_i32 s14, s11, 6
	v_and_b32_e32 v40, 63, v34
	s_mul_i32 s11, s14, 0x3000
	s_add_i32 s11, s11, 0
	s_mov_b32 s28, s56
	s_cmpk_lt_i32 s16, 0x800
	v_readlane_b32 s19, v254, 10
	s_waitcnt vmcnt(0)
	ds_write2st64_b32 v6, v0, v4 offset0:32 offset1:40
	v_lshl_add_u64 v[4:5], s[80:81], 0, v[2:3]
	global_load_dword v0, v[4:5], off
	v_lshl_add_u64 v[4:5], s[82:83], 0, v[2:3]
	global_load_dword v4, v[4:5], off
	v_readlane_b32 s68, v254, 45
	v_readlane_b32 s69, v254, 46
	v_readlane_b32 s70, v254, 47
	v_readlane_b32 s71, v254, 48
	v_lshl_add_u64 v[2:3], s[68:69], 0, v[2:3]
	v_readlane_b32 s72, v254, 49
	v_readlane_b32 s73, v254, 50
	v_readlane_b32 s74, v254, 51
	v_readlane_b32 s75, v254, 52
	v_readlane_b32 s76, v254, 53
	v_readlane_b32 s77, v254, 54
	v_readlane_b32 s78, v254, 55
	v_readlane_b32 s79, v254, 56
	v_readlane_b32 s80, v254, 57
	v_readlane_b32 s81, v254, 58
	v_readlane_b32 s82, v254, 59
	v_readlane_b32 s83, v254, 60
	s_waitcnt vmcnt(0)
	ds_write2st64_b32 v6, v0, v4 offset0:48 offset1:56
	global_load_dword v0, v[2:3], off
	v_lshl_add_u64 v[2:3], v[34:35], 2, s[4:5]
	global_load_dword v4, v[2:3], off
	v_or_b32_e32 v35, s10, v171
	s_waitcnt vmcnt(0)
	ds_write2st64_b32 v6, v0, v4 offset0:64 offset1:72
	global_load_dword v0, v[2:3], off offset:2048
	v_add_co_u32_e32 v2, vcc, s25, v2
	s_nop 1
	v_addc_co_u32_e32 v3, vcc, 0, v3, vcc
	global_load_dword v2, v[2:3], off
	s_waitcnt vmcnt(0)
	ds_write2st64_b32 v6, v0, v2 offset0:80 offset1:88
	v_lshlrev_b32_e32 v0, 12, v41
	v_or_b32_e32 v45, 0x4000, v0
	s_waitcnt vmcnt(0)
	s_nop 0
	s_waitcnt vmcnt(0)
	s_nop 0
	s_waitcnt vmcnt(0)
	s_nop 0
	s_waitcnt vmcnt(0)
	s_waitcnt vmcnt(0)
	s_nop 0
	s_waitcnt vmcnt(0)
	s_nop 0
	s_waitcnt vmcnt(0)
	s_nop 0
	s_waitcnt vmcnt(0)
	s_nop 0
	s_waitcnt vmcnt(0)
	s_nop 0
	s_waitcnt vmcnt(0)
	s_nop 0
	s_waitcnt vmcnt(0)
	s_nop 0
	s_waitcnt vmcnt(0)
	v_lshlrev_b32_e32 v16, 4, v40
	v_add_u32_e32 v174, s11, v16
	s_nop 0
	s_waitcnt vmcnt(0)
	s_nop 0
	s_waitcnt vmcnt(0)
	s_nop 0
	s_waitcnt vmcnt(0)
	s_nop 0
	s_waitcnt vmcnt(0)
	s_nop 0
	s_waitcnt vmcnt(0)
	s_waitcnt vmcnt(0)
	s_nop 0
	s_waitcnt vmcnt(0)
	s_nop 0
	s_waitcnt vmcnt(0)
	s_nop 0
	s_waitcnt vmcnt(0)
	s_nop 0
	s_waitcnt vmcnt(0)
	s_nop 0
	s_waitcnt vmcnt(0)
	s_waitcnt vmcnt(0)
	s_nop 0
	s_waitcnt vmcnt(0)
	s_nop 0
	s_waitcnt vmcnt(0)
	s_nop 0
	s_waitcnt vmcnt(0)
	s_waitcnt vmcnt(0)
	s_nop 0
	s_waitcnt vmcnt(0)
	s_waitcnt vmcnt(0)
	s_nop 0
	s_waitcnt vmcnt(0)
	s_waitcnt vmcnt(0)
	s_nop 0
	s_waitcnt vmcnt(0)
	s_waitcnt vmcnt(0)
	s_nop 0
	s_waitcnt vmcnt(0)
	s_waitcnt vmcnt(0)
	s_nop 0
	s_waitcnt vmcnt(0)
	s_nop 0
	s_waitcnt vmcnt(0)
	s_nop 0
	s_waitcnt vmcnt(0)
	s_nop 0
	s_waitcnt vmcnt(0)
	s_nop 0
	s_waitcnt vmcnt(0)
	s_nop 0
	s_waitcnt vmcnt(0)
	s_nop 0
	s_waitcnt vmcnt(0)
	s_waitcnt vmcnt(0)
	s_nop 0
	s_waitcnt vmcnt(0)
	s_nop 0
	s_waitcnt vmcnt(0)
	s_nop 0
	s_waitcnt vmcnt(0)
	s_waitcnt vmcnt(0)
	s_nop 0
	s_waitcnt vmcnt(0)
	s_nop 0
	s_waitcnt vmcnt(0)
	s_nop 0
	s_waitcnt vmcnt(0)
	s_nop 0
	s_waitcnt vmcnt(0)
	s_nop 0
	s_waitcnt vmcnt(0)
	s_nop 0
	s_waitcnt vmcnt(0)
	s_nop 0
	s_waitcnt vmcnt(0)
	s_nop 0
	s_waitcnt vmcnt(0)
	s_nop 0
	s_waitcnt vmcnt(0)
	s_nop 0
	s_waitcnt vmcnt(0)
	s_nop 0
	s_waitcnt vmcnt(0)
	s_nop 0
	s_waitcnt vmcnt(0)
	s_nop 0
	s_waitcnt vmcnt(0)
	s_nop 0
	s_waitcnt vmcnt(0)
	s_nop 0
	s_waitcnt vmcnt(0)
	s_nop 0
	s_waitcnt vmcnt(0)
	s_nop 0
	s_waitcnt vmcnt(0)
	s_nop 0
	s_waitcnt vmcnt(0)
	s_nop 0
	s_waitcnt vmcnt(0)
	s_waitcnt vmcnt(0)
	s_nop 0
	v_add_u32_e32 v52, 0x630, v35
	s_waitcnt vmcnt(0)
	s_nop 0
	v_add_u32_e32 v53, 0x830, v35
	s_waitcnt vmcnt(0)
	s_nop 0
	v_add_u32_e32 v35, 0xe30, v35
	s_waitcnt vmcnt(0)
	s_nop 0
	s_waitcnt vmcnt(0)
	s_nop 0
	s_waitcnt vmcnt(0)
	s_nop 0
	s_waitcnt vmcnt(0)
	s_nop 0
	s_waitcnt vmcnt(0)
	v_add_u32_e32 v48, v35, v45
	v_ashrrev_i32_e32 v49, 31, v48
	v_lshl_add_u64 v[48:49], v[48:49], 2, s[6:7]
	s_nop 0
	s_waitcnt vmcnt(0)
	s_nop 0
	s_waitcnt vmcnt(0)
	s_waitcnt vmcnt(0)
	s_nop 0
	s_waitcnt vmcnt(0)
	s_waitcnt vmcnt(0)
	v_bfe_u32 v144, v34, 4, 2
	v_lshrrev_b32_e32 v145, 6, v34
	v_and_b32_e32 v146, 15, v34
	v_lshl_add_u32 v145, v145, 6, v146
	v_lshlrev_b32_e32 v145, 2, v145
	v_lshl_add_u32 v140, v144, 14, v145
	v_add_u32_e32 v141, 0x1000, v140
	v_add_u32_e32 v142, 0x2000, v140
	v_add_u32_e32 v143, 0x3000, v140
	v_mov_b32_e32 v84, v140
	v_mov_b32_e32 v85, v141
	v_mov_b32_e32 v86, v142
	v_mov_b32_e32 v87, v143
	v_add_u32_e32 v88, 0x10000, v140
	v_add_u32_e32 v89, 0x10000, v141
	v_add_u32_e32 v90, 0x10000, v142
	v_add_u32_e32 v91, 0x10000, v143
	v_add_u32_e32 v92, 0x20000, v140
	v_add_u32_e32 v93, 0x20000, v141
	v_add_u32_e32 v94, 0x20000, v142
	v_add_u32_e32 v95, 0x20000, v143
	s_waitcnt vmcnt(0)
	global_load_dword v100, v140, s[12:13]
	global_load_dword v101, v140, s[12:13] offset:2048
	global_load_dword v102, v141, s[12:13]
	global_load_dword v103, v141, s[12:13] offset:2048
	global_load_dword v104, v142, s[12:13]
	global_load_dword v105, v142, s[12:13] offset:2048
	global_load_dword v106, v143, s[12:13]
	global_load_dword v107, v143, s[12:13] offset:2048
	global_load_dword v108, v140, s[8:9]
	global_load_dword v109, v140, s[8:9] offset:2048
	global_load_dword v110, v141, s[8:9]
	global_load_dword v111, v141, s[8:9] offset:2048
	global_load_dword v112, v142, s[8:9]
	global_load_dword v113, v142, s[8:9] offset:2048
	global_load_dword v114, v143, s[8:9]
	global_load_dword v115, v143, s[8:9] offset:2048
	global_load_dword v116, v84, s[6:7]
	global_load_dword v117, v84, s[6:7] offset:2048
	global_load_dword v118, v85, s[6:7]
	global_load_dword v119, v85, s[6:7] offset:2048
	global_load_dword v120, v86, s[6:7]
	global_load_dword v121, v86, s[6:7] offset:2048
	global_load_dword v122, v87, s[6:7]
	global_load_dword v123, v87, s[6:7] offset:2048
	global_load_dword v124, v88, s[6:7]
	global_load_dword v125, v88, s[6:7] offset:2048
	global_load_dword v126, v89, s[6:7]
	global_load_dword v127, v89, s[6:7] offset:2048
	global_load_dword v128, v90, s[6:7]
	global_load_dword v129, v90, s[6:7] offset:2048
	global_load_dword v130, v91, s[6:7]
	global_load_dword v131, v91, s[6:7] offset:2048
	global_load_dword v132, v92, s[6:7]
	global_load_dword v133, v92, s[6:7] offset:2048
	global_load_dword v134, v93, s[6:7]
	global_load_dword v135, v93, s[6:7] offset:2048
	global_load_dword v136, v94, s[6:7]
	global_load_dword v137, v94, s[6:7] offset:2048
	global_load_dword v138, v95, s[6:7]
	global_load_dword v139, v95, s[6:7] offset:2048
	global_load_dword v176, v140, s[12:13] offset:64
	global_load_dword v177, v140, s[12:13] offset:2112
	global_load_dword v178, v141, s[12:13] offset:64
	global_load_dword v179, v141, s[12:13] offset:2112
	global_load_dword v180, v142, s[12:13] offset:64
	global_load_dword v181, v142, s[12:13] offset:2112
	global_load_dword v182, v143, s[12:13] offset:64
	global_load_dword v183, v143, s[12:13] offset:2112
	global_load_dword v184, v140, s[8:9] offset:64
	global_load_dword v185, v140, s[8:9] offset:2112
	global_load_dword v186, v141, s[8:9] offset:64
	global_load_dword v187, v141, s[8:9] offset:2112
	global_load_dword v188, v142, s[8:9] offset:64
	global_load_dword v189, v142, s[8:9] offset:2112
	global_load_dword v190, v143, s[8:9] offset:64
	global_load_dword v191, v143, s[8:9] offset:2112
	global_load_dword v192, v84, s[6:7] offset:64
	global_load_dword v193, v84, s[6:7] offset:2112
	global_load_dword v194, v85, s[6:7] offset:64
	global_load_dword v195, v85, s[6:7] offset:2112
	global_load_dword v196, v86, s[6:7] offset:64
	global_load_dword v197, v86, s[6:7] offset:2112
	global_load_dword v198, v87, s[6:7] offset:64
	global_load_dword v199, v87, s[6:7] offset:2112
	global_load_dword v200, v88, s[6:7] offset:64
	global_load_dword v201, v88, s[6:7] offset:2112
	global_load_dword v202, v89, s[6:7] offset:64
	global_load_dword v203, v89, s[6:7] offset:2112
	global_load_dword v204, v90, s[6:7] offset:64
	global_load_dword v205, v90, s[6:7] offset:2112
	global_load_dword v206, v91, s[6:7] offset:64
	global_load_dword v207, v91, s[6:7] offset:2112
	global_load_dword v208, v92, s[6:7] offset:64
	global_load_dword v209, v92, s[6:7] offset:2112
	global_load_dword v210, v93, s[6:7] offset:64
	global_load_dword v211, v93, s[6:7] offset:2112
	global_load_dword v220, v94, s[6:7] offset:64
	global_load_dword v221, v94, s[6:7] offset:2112
	global_load_dword v222, v95, s[6:7] offset:64
	global_load_dword v223, v95, s[6:7] offset:2112
	s_waitcnt vmcnt(40)
	v_cvt_pk_bf16_f32 v2, v100, v101
	v_cvt_pk_bf16_f32 v3, v102, v103
	v_cvt_pk_bf16_f32 v4, v104, v105
	v_cvt_pk_bf16_f32 v5, v106, v107
	v_cvt_pk_bf16_f32 v6, v108, v109
	v_cvt_pk_bf16_f32 v7, v110, v111
	v_cvt_pk_bf16_f32 v8, v112, v113
	v_cvt_pk_bf16_f32 v9, v114, v115
	v_cvt_pk_bf16_f32 v64, v116, v117
	v_cvt_pk_bf16_f32 v65, v118, v119
	v_cvt_pk_bf16_f32 v66, v120, v121
	v_cvt_pk_bf16_f32 v67, v122, v123
	ds_write_b128 v174, v[64:67] offset:32768
	v_cvt_pk_bf16_f32 v68, v124, v125
	v_cvt_pk_bf16_f32 v69, v126, v127
	v_cvt_pk_bf16_f32 v70, v128, v129
	v_cvt_pk_bf16_f32 v71, v130, v131
	ds_write_b128 v174, v[68:71] offset:36864
	v_cvt_pk_bf16_f32 v72, v132, v133
	v_cvt_pk_bf16_f32 v73, v134, v135
	v_cvt_pk_bf16_f32 v74, v136, v137
	v_cvt_pk_bf16_f32 v75, v138, v139
	ds_write_b128 v174, v[72:75] offset:40960
	global_load_dword v100, v140, s[12:13] offset:128
	global_load_dword v101, v140, s[12:13] offset:2176
	global_load_dword v102, v141, s[12:13] offset:128
	global_load_dword v103, v141, s[12:13] offset:2176
	global_load_dword v104, v142, s[12:13] offset:128
	global_load_dword v105, v142, s[12:13] offset:2176
	global_load_dword v106, v143, s[12:13] offset:128
	global_load_dword v107, v143, s[12:13] offset:2176
	global_load_dword v108, v140, s[8:9] offset:128
	global_load_dword v109, v140, s[8:9] offset:2176
	global_load_dword v110, v141, s[8:9] offset:128
	global_load_dword v111, v141, s[8:9] offset:2176
	global_load_dword v112, v142, s[8:9] offset:128
	global_load_dword v113, v142, s[8:9] offset:2176
	global_load_dword v114, v143, s[8:9] offset:128
	global_load_dword v115, v143, s[8:9] offset:2176
	global_load_dword v116, v84, s[6:7] offset:128
	global_load_dword v117, v84, s[6:7] offset:2176
	global_load_dword v118, v85, s[6:7] offset:128
	global_load_dword v119, v85, s[6:7] offset:2176
	global_load_dword v120, v86, s[6:7] offset:128
	global_load_dword v121, v86, s[6:7] offset:2176
	global_load_dword v122, v87, s[6:7] offset:128
	global_load_dword v123, v87, s[6:7] offset:2176
	global_load_dword v124, v88, s[6:7] offset:128
	global_load_dword v125, v88, s[6:7] offset:2176
	global_load_dword v126, v89, s[6:7] offset:128
	global_load_dword v127, v89, s[6:7] offset:2176
	global_load_dword v128, v90, s[6:7] offset:128
	global_load_dword v129, v90, s[6:7] offset:2176
	global_load_dword v130, v91, s[6:7] offset:128
	global_load_dword v131, v91, s[6:7] offset:2176
	global_load_dword v132, v92, s[6:7] offset:128
	global_load_dword v133, v92, s[6:7] offset:2176
	global_load_dword v134, v93, s[6:7] offset:128
	global_load_dword v135, v93, s[6:7] offset:2176
	global_load_dword v136, v94, s[6:7] offset:128
	global_load_dword v137, v94, s[6:7] offset:2176
	global_load_dword v138, v95, s[6:7] offset:128
	global_load_dword v139, v95, s[6:7] offset:2176
	s_waitcnt vmcnt(40)
	v_cvt_pk_bf16_f32 v10, v176, v177
	v_cvt_pk_bf16_f32 v11, v178, v179
	v_cvt_pk_bf16_f32 v12, v180, v181
	v_cvt_pk_bf16_f32 v13, v182, v183
	v_cvt_pk_bf16_f32 v14, v184, v185
	v_cvt_pk_bf16_f32 v15, v186, v187
	v_cvt_pk_bf16_f32 v16, v188, v189
	v_cvt_pk_bf16_f32 v17, v190, v191
	v_cvt_pk_bf16_f32 v64, v192, v193
	v_cvt_pk_bf16_f32 v65, v194, v195
	v_cvt_pk_bf16_f32 v66, v196, v197
	v_cvt_pk_bf16_f32 v67, v198, v199
	ds_write_b128 v174, v[64:67] offset:33792
	v_cvt_pk_bf16_f32 v68, v200, v201
	v_cvt_pk_bf16_f32 v69, v202, v203
	v_cvt_pk_bf16_f32 v70, v204, v205
	v_cvt_pk_bf16_f32 v71, v206, v207
	ds_write_b128 v174, v[68:71] offset:37888
	v_cvt_pk_bf16_f32 v72, v208, v209
	v_cvt_pk_bf16_f32 v73, v210, v211
	v_cvt_pk_bf16_f32 v74, v220, v221
	v_cvt_pk_bf16_f32 v75, v222, v223
	ds_write_b128 v174, v[72:75] offset:41984
	global_load_dword v176, v140, s[12:13] offset:192
	global_load_dword v177, v140, s[12:13] offset:2240
	global_load_dword v178, v141, s[12:13] offset:192
	global_load_dword v179, v141, s[12:13] offset:2240
	global_load_dword v180, v142, s[12:13] offset:192
	global_load_dword v181, v142, s[12:13] offset:2240
	global_load_dword v182, v143, s[12:13] offset:192
	global_load_dword v183, v143, s[12:13] offset:2240
	global_load_dword v184, v140, s[8:9] offset:192
	global_load_dword v185, v140, s[8:9] offset:2240
	global_load_dword v186, v141, s[8:9] offset:192
	global_load_dword v187, v141, s[8:9] offset:2240
	global_load_dword v188, v142, s[8:9] offset:192
	global_load_dword v189, v142, s[8:9] offset:2240
	global_load_dword v190, v143, s[8:9] offset:192
	global_load_dword v191, v143, s[8:9] offset:2240
	global_load_dword v192, v84, s[6:7] offset:192
	global_load_dword v193, v84, s[6:7] offset:2240
	global_load_dword v194, v85, s[6:7] offset:192
	global_load_dword v195, v85, s[6:7] offset:2240
	global_load_dword v196, v86, s[6:7] offset:192
	global_load_dword v197, v86, s[6:7] offset:2240
	global_load_dword v198, v87, s[6:7] offset:192
	global_load_dword v199, v87, s[6:7] offset:2240
	global_load_dword v200, v88, s[6:7] offset:192
	global_load_dword v201, v88, s[6:7] offset:2240
	global_load_dword v202, v89, s[6:7] offset:192
	global_load_dword v203, v89, s[6:7] offset:2240
	global_load_dword v204, v90, s[6:7] offset:192
	global_load_dword v205, v90, s[6:7] offset:2240
	global_load_dword v206, v91, s[6:7] offset:192
	global_load_dword v207, v91, s[6:7] offset:2240
	global_load_dword v208, v92, s[6:7] offset:192
	global_load_dword v209, v92, s[6:7] offset:2240
	global_load_dword v210, v93, s[6:7] offset:192
	global_load_dword v211, v93, s[6:7] offset:2240
	global_load_dword v220, v94, s[6:7] offset:192
	global_load_dword v221, v94, s[6:7] offset:2240
	global_load_dword v222, v95, s[6:7] offset:192
	global_load_dword v223, v95, s[6:7] offset:2240
	s_waitcnt vmcnt(40)
	v_cvt_pk_bf16_f32 v18, v100, v101
	v_cvt_pk_bf16_f32 v19, v102, v103
	v_cvt_pk_bf16_f32 v20, v104, v105
	v_cvt_pk_bf16_f32 v21, v106, v107
	v_cvt_pk_bf16_f32 v22, v108, v109
	v_cvt_pk_bf16_f32 v23, v110, v111
	v_cvt_pk_bf16_f32 v24, v112, v113
	v_cvt_pk_bf16_f32 v25, v114, v115
	v_cvt_pk_bf16_f32 v64, v116, v117
	v_cvt_pk_bf16_f32 v65, v118, v119
	v_cvt_pk_bf16_f32 v66, v120, v121
	v_cvt_pk_bf16_f32 v67, v122, v123
	ds_write_b128 v174, v[64:67] offset:34816
	v_cvt_pk_bf16_f32 v68, v124, v125
	v_cvt_pk_bf16_f32 v69, v126, v127
	v_cvt_pk_bf16_f32 v70, v128, v129
	v_cvt_pk_bf16_f32 v71, v130, v131
	ds_write_b128 v174, v[68:71] offset:38912
	v_cvt_pk_bf16_f32 v72, v132, v133
	v_cvt_pk_bf16_f32 v73, v134, v135
	v_cvt_pk_bf16_f32 v74, v136, v137
	v_cvt_pk_bf16_f32 v75, v138, v139
	ds_write_b128 v174, v[72:75] offset:43008
	s_waitcnt vmcnt(0)
	v_cvt_pk_bf16_f32 v26, v176, v177
	v_cvt_pk_bf16_f32 v27, v178, v179
	v_cvt_pk_bf16_f32 v28, v180, v181
	v_cvt_pk_bf16_f32 v29, v182, v183
	v_cvt_pk_bf16_f32 v30, v184, v185
	v_cvt_pk_bf16_f32 v31, v186, v187
	v_cvt_pk_bf16_f32 v32, v188, v189
	v_cvt_pk_bf16_f32 v33, v190, v191
	v_cvt_pk_bf16_f32 v64, v192, v193
	v_cvt_pk_bf16_f32 v65, v194, v195
	v_cvt_pk_bf16_f32 v66, v196, v197
	v_cvt_pk_bf16_f32 v67, v198, v199
	ds_write_b128 v174, v[64:67] offset:35840
	v_cvt_pk_bf16_f32 v68, v200, v201
	v_cvt_pk_bf16_f32 v69, v202, v203
	v_cvt_pk_bf16_f32 v70, v204, v205
	v_cvt_pk_bf16_f32 v71, v206, v207
	ds_write_b128 v174, v[68:71] offset:39936
	v_cvt_pk_bf16_f32 v72, v208, v209
	v_cvt_pk_bf16_f32 v73, v210, v211
	v_cvt_pk_bf16_f32 v74, v220, v221
	v_cvt_pk_bf16_f32 v75, v222, v223
	ds_write_b128 v174, v[72:75] offset:44032
	s_waitcnt lgkmcnt(0)
	s_barrier
	s_cbranch_scc0 .LBB0_882
	s_movk_i32 s6, 0x140
	v_cmp_gt_i32_e32 vcc, s6, v34
	s_mov_b32 s6, 0x66666667
	v_mul_hi_i32 v0, v34, s6
	v_lshrrev_b32_e32 v35, 31, v0
	v_ashrrev_i32_e32 v0, 3, v0
	v_add_u32_e32 v175, v0, v35
	s_movk_i32 s6, 0xffec
	v_mad_u64_u32 v[36:37], s[6:7], v175, s6, v[34:35]
	s_ashr_i32 s11, s10, 31
	v_lshlrev_b32_e32 v38, 3, v36
	s_lshl_b64 s[8:9], s[10:11], 1
	v_ashrrev_i32_e32 v39, 31, v38
	s_movk_i32 s12, 0x150
	s_add_u32 s8, s48, s8
	v_lshl_add_u64 v[42:43], v[38:39], 2, s[4:5]
	s_mov_b64 s[4:5], 0x1800
	v_mul_lo_u32 v0, v175, s12
	v_lshlrev_b32_e32 v35, 4, v36
	s_addc_u32 s9, s49, s9
	s_ashr_i32 s15, s14, 31
	s_lshl_b32 s10, s10, 2
	s_ashr_i32 s17, s16, 31
	v_lshl_add_u64 v[98:99], v[42:43], 0, s[4:5]
	v_cmp_lt_i32_e64 s[4:5], 3, v36
	v_cmp_gt_u32_e64 s[6:7], 8, v36
	v_add3_u32 v176, 0, v0, v35
	v_mad_u32_u24 v35, v171, s12, 0
	s_lshl_b64 s[12:13], s[14:15], 11
	v_lshl_or_b32 v36, v41, 4, s10
	s_lshl_b32 s15, s16, 4
	s_lshl_b32 s24, s18, 4
	s_lshl_b64 s[10:11], s[16:17], 14
	s_add_u32 s10, s10, s12
	v_lshlrev_b32_e32 v0, 3, v41
	s_addc_u32 s11, s11, s13
	v_readlane_b32 s12, v255, 19
	v_lshl_add_u64 v[100:101], s[8:9], 0, v[0:1]
	v_lshlrev_b32_e32 v0, 2, v40
	s_add_u32 s10, s12, s10
	v_readlane_b32 s12, v255, 20
	v_and_b32_e32 v34, 48, v34
	v_xor_b32_e32 v177, 64, v0
	v_xor_b32_e32 v178, 0x80, v0
	v_lshlrev_b32_e32 v0, 3, v40
	s_addc_u32 s11, s12, s11
	s_ashr_i32 s19, s18, 31
	v_lshl_add_u64 v[102:103], s[60:61], 0, v[0:1]
	v_cmp_gt_u32_e64 s[8:9], 16, v40
	v_add_u32_e32 v179, 0, v36
	v_lshl_add_u64 v[104:105], v[38:39], 1, s[48:49]
	v_lshl_add_u64 v[106:107], s[10:11], 0, v[0:1]
	s_lshl_b64 s[20:21], s[18:19], 14
	v_add_u32_e32 v180, v35, v34
	s_movk_i32 s17, 0xe00
	s_branch .LBB0_846
